# neighbourhood attention: the 16+4 rpb bias LDS reads of each key half issued as one batch for all lanes with counted lgkmcnt, window mask applied by v_cndmask instead of per-element exec-masked branch
# speedup vs baseline: 1.0839x; 1.0047x over previous
; template <bool NA, bool FIXED> ...
;     ...
;       if (NA && latent) {
;         const float* brow_ = btab + (tile - r + 7) * 31;
;         const int kcb = s2 * 32 + hl * 4;
; #pragma unroll
;         for (int i = 0; i < 16; ++i) {
;           int kc = kcb + 8 * (i >> 2) + (i & 3);
;           bool valid = (kc >= w0) && (kc < w0 + 16);
;           int dx = min(max(kc - qcol, -15), 15) + 15;
;           float bv = brow_[dx];
;           sc[i] = valid ? sc[i] * cs + bv : -1e30f;
;         }
;         tmax = fmaxf(fmaxf(sc[0], sc[1]), fmaxf(sc[2], sc[3]));
; #pragma unroll
;         for (int i = 4; i < 16; i += 4) tmax = fmaxf(tmax, fmaxf(fmaxf(sc[i], sc[i + 1]), fmaxf(sc[i + 2], sc[i + 3])));
.LBB0_353:
	s_nop 8
	v_mov_b64_e32 v[110:111], v[94:95]
	s_andn2_b64 vcc, exec, s[92:93]
	v_mov_b64_e32 v[108:109], v[92:93]
	v_mov_b64_e32 v[106:107], v[90:91]
	v_mov_b64_e32 v[104:105], v[88:89]
	v_mov_b64_e32 v[102:103], v[86:87]
	v_mov_b64_e32 v[100:101], v[84:85]
	v_mov_b64_e32 v[98:99], v[82:83]
	v_mov_b64_e32 v[96:97], v[80:81]
	s_cbranch_vccnz .LBB0_387
	v_add_u32_e32 v96, s37, v178
	v_add_u32_e32 v97, s37, v177
	v_add_u32_e32 v98, s37, v176
	v_add_u32_e32 v99, s37, v175
	v_add_u32_e32 v100, s37, v174
	v_add_u32_e32 v101, s37, v173
	v_add_u32_e32 v102, s37, v172
	v_add_u32_e32 v103, s37, v171
	v_add_u32_e32 v104, s37, v163
	v_add_u32_e32 v105, s37, v164
	v_add_u32_e32 v106, s37, v165
	v_add_u32_e32 v107, s37, v166
	v_add_u32_e32 v108, s37, v167
	v_add_u32_e32 v109, s37, v168
	v_add_u32_e32 v110, s37, v169
	v_add_u32_e32 v111, s37, v170
	ds_read_b32 v96, v96
	ds_read_b32 v97, v97
	ds_read_b32 v98, v98
	ds_read_b32 v99, v99
	ds_read_b32 v100, v100
	ds_read_b32 v101, v101
	ds_read_b32 v102, v102
	ds_read_b32 v103, v103
	ds_read_b32 v104, v104
	ds_read_b32 v105, v105
	ds_read_b32 v106, v106
	ds_read_b32 v107, v107
	ds_read_b32 v108, v108
	ds_read_b32 v109, v109
	ds_read_b32 v110, v110
	ds_read_b32 v111, v111
	v_mov_b32_e32 v0, 0xf149f2ca
	s_waitcnt lgkmcnt(15)
	v_readlane_b32 vcc_lo, v255, 21
	v_readlane_b32 vcc_hi, v255, 22
	v_fmac_f32_e32 v96, 0x3e38aa3b, v80
	s_nop 1
	v_cndmask_b32_e32 v96, v0, v96, vcc
	s_waitcnt lgkmcnt(14)
	v_readlane_b32 vcc_lo, v255, 23
	v_readlane_b32 vcc_hi, v255, 24
	v_fmac_f32_e32 v97, 0x3e38aa3b, v81
	s_nop 1
	v_cndmask_b32_e32 v97, v0, v97, vcc
	s_waitcnt lgkmcnt(13)
	v_readlane_b32 vcc_lo, v255, 25
	v_readlane_b32 vcc_hi, v255, 26
	v_fmac_f32_e32 v98, 0x3e38aa3b, v82
	s_nop 1
	v_cndmask_b32_e32 v98, v0, v98, vcc
	s_waitcnt lgkmcnt(12)
	v_readlane_b32 vcc_lo, v255, 27
	v_readlane_b32 vcc_hi, v255, 28
	v_fmac_f32_e32 v99, 0x3e38aa3b, v83
	s_nop 1
	v_cndmask_b32_e32 v99, v0, v99, vcc
	s_waitcnt lgkmcnt(11)
	v_readlane_b32 vcc_lo, v255, 29
	v_readlane_b32 vcc_hi, v255, 30
	v_fmac_f32_e32 v100, 0x3e38aa3b, v84
	s_nop 1
	v_cndmask_b32_e32 v100, v0, v100, vcc
	s_waitcnt lgkmcnt(10)
	v_readlane_b32 vcc_lo, v255, 31
	v_readlane_b32 vcc_hi, v255, 32
	v_fmac_f32_e32 v101, 0x3e38aa3b, v85
	s_nop 1
	v_cndmask_b32_e32 v101, v0, v101, vcc
	s_waitcnt lgkmcnt(9)
	v_fmac_f32_e32 v102, 0x3e38aa3b, v86
	v_cndmask_b32_e64 v102, v0, v102, s[48:49]
	s_waitcnt lgkmcnt(8)
	v_fmac_f32_e32 v103, 0x3e38aa3b, v87
	v_cndmask_b32_e64 v103, v0, v103, s[50:51]
	s_waitcnt lgkmcnt(7)
	v_fmac_f32_e32 v104, 0x3e38aa3b, v88
	v_cndmask_b32_e64 v104, v0, v104, s[2:3]
	s_waitcnt lgkmcnt(6)
	v_fmac_f32_e32 v105, 0x3e38aa3b, v89
	v_cndmask_b32_e64 v105, v0, v105, s[34:35]
	s_waitcnt lgkmcnt(5)
	v_fmac_f32_e32 v106, 0x3e38aa3b, v90
	v_cndmask_b32_e64 v106, v0, v106, s[4:5]
	s_waitcnt lgkmcnt(4)
	v_fmac_f32_e32 v107, 0x3e38aa3b, v91
	v_cndmask_b32_e64 v107, v0, v107, s[6:7]
	s_waitcnt lgkmcnt(3)
	v_fmac_f32_e32 v108, 0x3e38aa3b, v92
	v_cndmask_b32_e64 v108, v0, v108, s[8:9]
	s_waitcnt lgkmcnt(2)
	v_fmac_f32_e32 v109, 0x3e38aa3b, v93
	v_cndmask_b32_e64 v109, v0, v109, s[10:11]
	s_waitcnt lgkmcnt(1)
	v_fmac_f32_e32 v110, 0x3e38aa3b, v94
	v_cndmask_b32_e64 v110, v0, v110, s[12:13]
	s_waitcnt lgkmcnt(0)
	v_fmac_f32_e32 v111, 0x3e38aa3b, v95
	v_cndmask_b32_e64 v111, v0, v111, s[14:15]
	s_mov_b64 s[92:93], exec
	v_max_f32_e32 v0, v97, v97
	v_max_f32_e32 v2, v96, v96
	v_max_f32_e32 v0, v2, v0
	v_max_f32_e32 v2, v99, v99
	v_max_f32_e32 v3, v98, v98
	v_max_f32_e32 v2, v3, v2
	v_max_f32_e32 v3, v103, v103
	v_max_f32_e32 v4, v102, v102
	v_max_f32_e32 v3, v4, v3
	v_max3_f32 v3, v100, v101, v3
	v_max3_f32 v0, v0, v2, v3
	v_max_f32_e32 v2, v107, v107
	v_max_f32_e32 v3, v106, v106
	v_max_f32_e32 v2, v3, v2
	v_max_f32_e32 v3, v111, v111
	v_max_f32_e32 v4, v110, v110
	v_max_f32_e32 v3, v4, v3
	v_max3_f32 v2, v104, v105, v2
	v_max3_f32 v3, v108, v109, v3
	v_max3_f32 v0, v0, v2, v3

; DI float shx(float v, int mask, int lane) { return __int_as_float(__builtin_amdgcn_ds_bpermute((lane ^ mask) << 2, __float_as_int(v))); }
; template <int I0, int I1>
; DI void na_softmax(f32x16& sc, f32x16& o0, f32x16& o1, float& mrun, float& lsum, const float* __restrict__ brow_, const int kcb,
;                    const int w0, const int qcol, const float cs, const int lane) {
; #pragma unroll
;   for (int i = I0; i < I1; ++i) {
;     const int kc = kcb + 8 * (i >> 2) + (i & 3);
;     const bool valid = (kc >= w0) && (kc < w0 + 16);
;     const int dx = min(max(kc - qcol, -15), 15) + 15;
;     const float bv = brow_[dx];
;     sc[i] = valid ? sc[i] * cs + bv : -1e30f;
;   }
;   float tmax = sc[I0];
; #pragma unroll
;   for (int i = I0 + 1; i < I1; ++i) tmax = fmaxf(tmax, sc[i]);
;   tmax = fmaxf(tmax, shx(tmax, 32, lane));
;   if (__builtin_amdgcn_ballot_w64(tmax > mrun + 4.f) != 0ull) {
;     const float mnew = fmaxf(mrun, tmax);
;     const float alpha = __builtin_amdgcn_exp2f(mrun - mnew);
;     mrun = mnew;
;     lsum *= alpha;
; #pragma unroll
;     for (int i = 0; i < 16; ++i) { o0[i] *= alpha; o1[i] *= alpha; }
;   }
.LBB0_390:
	s_sub_i32 s46, s46, s20
	s_mulk_i32 s46, 0x7c
	s_add_i32 s46, s46, 0
	s_add_i32 s46, s46, 0x10000
	s_and_b64 vcc, exec, s[92:93]
	s_cbranch_vccz .LBB0_402
	v_lshl_add_u32 v2, v143, 2, s46
	v_lshl_add_u32 v0, v144, 2, s46
	v_lshl_add_u32 v5, v145, 2, s46
	v_lshl_add_u32 v4, v148, 2, s46
	ds_read_b32 v2, v2 offset:928
	ds_read_b32 v0, v0 offset:928
	ds_read_b32 v5, v5 offset:928
	ds_read_b32 v4, v4 offset:928
	v_mov_b32_e32 v3, 0xf149f2ca
	s_waitcnt lgkmcnt(3)
	v_fmac_f32_e32 v2, 0x3e38aa3b, v92
	v_cndmask_b32_e64 v2, v3, v2, s[8:9]
	s_waitcnt lgkmcnt(2)
	v_fmac_f32_e32 v0, 0x3e38aa3b, v93
	v_cndmask_b32_e64 v0, v3, v0, s[10:11]
	s_waitcnt lgkmcnt(1)
	v_fmac_f32_e32 v5, 0x3e38aa3b, v94
	v_cndmask_b32_e64 v5, v3, v5, s[12:13]
	s_waitcnt lgkmcnt(0)
	v_fmac_f32_e32 v4, 0x3e38aa3b, v95
	v_cndmask_b32_e64 v4, v3, v4, s[14:15]
	s_mov_b64 s[92:93], exec
	v_max_f32_e32 v3, v0, v0
	v_max_f32_e32 v6, v2, v2
	v_max_f32_e32 v3, v6, v3
	v_max3_f32 v3, v3, v5, v4
	ds_bpermute_b32 v6, v136, v3
	s_waitcnt lgkmcnt(0)
	v_max_f32_e32 v6, v6, v6
	v_max_f32_e32 v3, v3, v6
	v_add_f32_e32 v6, 4.0, v132
	v_cmp_gt_f32_e32 vcc, v3, v6
	s_cbranch_vccz .LBB0_401
	v_max_f32_e32 v3, v3, v3
	v_max_f32_e32 v6, v132, v132
	v_max_f32_e32 v3, v6, v3
	v_sub_f32_e32 v6, v132, v3
	v_exp_f32_e32 v6, v6
	v_mov_b32_e32 v132, v3
	v_mul_f32_e32 v195, v195, v6
	v_pk_mul_f32 v[30:31], v[30:31], v[6:7] op_sel_hi:[1,0]
	v_pk_mul_f32 v[28:29], v[28:29], v[6:7] op_sel_hi:[1,0]
	v_pk_mul_f32 v[26:27], v[26:27], v[6:7] op_sel_hi:[1,0]
	v_pk_mul_f32 v[24:25], v[24:25], v[6:7] op_sel_hi:[1,0]
	v_pk_mul_f32 v[22:23], v[22:23], v[6:7] op_sel_hi:[1,0]
	v_pk_mul_f32 v[20:21], v[20:21], v[6:7] op_sel_hi:[1,0]
	v_pk_mul_f32 v[18:19], v[18:19], v[6:7] op_sel_hi:[1,0]
	v_pk_mul_f32 v[16:17], v[16:17], v[6:7] op_sel_hi:[1,0]
	v_pk_mul_f32 v[46:47], v[46:47], v[6:7] op_sel_hi:[1,0]
	v_pk_mul_f32 v[44:45], v[44:45], v[6:7] op_sel_hi:[1,0]
	v_pk_mul_f32 v[42:43], v[42:43], v[6:7] op_sel_hi:[1,0]
	v_pk_mul_f32 v[40:41], v[40:41], v[6:7] op_sel_hi:[1,0]
	v_pk_mul_f32 v[38:39], v[38:39], v[6:7] op_sel_hi:[1,0]
	v_pk_mul_f32 v[36:37], v[36:37], v[6:7] op_sel_hi:[1,0]
	v_pk_mul_f32 v[34:35], v[34:35], v[6:7] op_sel_hi:[1,0]
	v_pk_mul_f32 v[32:33], v[32:33], v[6:7] op_sel_hi:[1,0]

; template <bool NA, bool FIXED> ...
;     ...
;       if (NA && latent) {
;         const float* brow_ = btab + (tile - r + 7) * 31;
;         const int kcb = s2 * 32 + hl * 4;
; #pragma unroll
;         for (int i = 0; i < 16; ++i) {
;           int kc = kcb + 8 * (i >> 2) + (i & 3);
;           bool valid = (kc >= w0) && (kc < w0 + 16);
;           int dx = min(max(kc - qcol, -15), 15) + 15;
;           float bv = brow_[dx];
;           sc[i] = valid ? sc[i] * cs + bv : -1e30f;
;         }
;         tmax = fmaxf(fmaxf(sc[0], sc[1]), fmaxf(sc[2], sc[3]));
; #pragma unroll
;         for (int i = 4; i < 16; i += 4) tmax = fmaxf(tmax, fmaxf(fmaxf(sc[i], sc[i + 1]), fmaxf(sc[i + 2], sc[i + 3])));
.LBB0_405:
	s_nop 8
	v_mov_b64_e32 v[110:111], v[94:95]
	s_andn2_b64 vcc, exec, s[16:17]
	v_mov_b64_e32 v[108:109], v[92:93]
	v_mov_b64_e32 v[106:107], v[90:91]
	v_mov_b64_e32 v[104:105], v[88:89]
	v_mov_b64_e32 v[102:103], v[86:87]
	v_mov_b64_e32 v[100:101], v[84:85]
	v_mov_b64_e32 v[98:99], v[82:83]
	v_mov_b64_e32 v[96:97], v[80:81]
	s_cbranch_vccnz .LBB0_439
	v_add_u32_e32 v96, s37, v179
	v_add_u32_e32 v97, s37, v180
	v_add_u32_e32 v98, s37, v181
	v_add_u32_e32 v99, s37, v182
	v_add_u32_e32 v100, s37, v183
	v_add_u32_e32 v101, s37, v184
	v_add_u32_e32 v102, s37, v185
	v_add_u32_e32 v103, s37, v186
	v_add_u32_e32 v104, s37, v187
	v_add_u32_e32 v105, s37, v188
	v_add_u32_e32 v106, s37, v189
	v_add_u32_e32 v107, s37, v190
	v_add_u32_e32 v108, s37, v191
	v_add_u32_e32 v109, s37, v192
	v_add_u32_e32 v110, s37, v193
	v_add_u32_e32 v111, s37, v194
	ds_read_b32 v96, v96
	ds_read_b32 v97, v97
	ds_read_b32 v98, v98
	ds_read_b32 v99, v99
	ds_read_b32 v100, v100
	ds_read_b32 v101, v101
	ds_read_b32 v102, v102
	ds_read_b32 v103, v103
	ds_read_b32 v104, v104
	ds_read_b32 v105, v105
	ds_read_b32 v106, v106
	ds_read_b32 v107, v107
	ds_read_b32 v108, v108
	ds_read_b32 v109, v109
	ds_read_b32 v110, v110
	ds_read_b32 v111, v111
	v_mov_b32_e32 v2, 0xf149f2ca
	s_waitcnt lgkmcnt(15)
	v_fmac_f32_e32 v96, 0x3e38aa3b, v80
	v_cndmask_b32_e64 v96, v2, v96, s[18:19]
	s_waitcnt lgkmcnt(14)
	v_fmac_f32_e32 v97, 0x3e38aa3b, v81
	v_cndmask_b32_e64 v97, v2, v97, s[68:69]
	s_waitcnt lgkmcnt(13)
	v_fmac_f32_e32 v98, 0x3e38aa3b, v82
	v_cndmask_b32_e64 v98, v2, v98, s[70:71]
	s_waitcnt lgkmcnt(12)
	v_fmac_f32_e32 v99, 0x3e38aa3b, v83
	v_cndmask_b32_e64 v99, v2, v99, s[22:23]
	s_waitcnt lgkmcnt(11)
	v_fmac_f32_e32 v100, 0x3e38aa3b, v84
	v_cndmask_b32_e64 v100, v2, v100, s[28:29]
	s_waitcnt lgkmcnt(10)
	v_fmac_f32_e32 v101, 0x3e38aa3b, v85
	v_cndmask_b32_e64 v101, v2, v101, s[30:31]
	s_waitcnt lgkmcnt(9)
	v_fmac_f32_e32 v102, 0x3e38aa3b, v86
	v_cndmask_b32_e64 v102, v2, v102, s[88:89]
	s_waitcnt lgkmcnt(8)
	v_fmac_f32_e32 v103, 0x3e38aa3b, v87
	v_cndmask_b32_e64 v103, v2, v103, s[0:1]
	s_waitcnt lgkmcnt(7)
	v_fmac_f32_e32 v104, 0x3e38aa3b, v88
	v_cndmask_b32_e64 v104, v2, v104, s[52:53]
	s_waitcnt lgkmcnt(6)
	v_fmac_f32_e32 v105, 0x3e38aa3b, v89
	v_cndmask_b32_e64 v105, v2, v105, s[54:55]
	s_waitcnt lgkmcnt(5)
	v_fmac_f32_e32 v106, 0x3e38aa3b, v90
	v_cndmask_b32_e64 v106, v2, v106, s[56:57]
	s_waitcnt lgkmcnt(4)
	v_fmac_f32_e32 v107, 0x3e38aa3b, v91
	v_cndmask_b32_e64 v107, v2, v107, s[58:59]
	s_waitcnt lgkmcnt(3)
	v_fmac_f32_e32 v108, 0x3e38aa3b, v92
	v_cndmask_b32_e64 v108, v2, v108, s[60:61]
	s_waitcnt lgkmcnt(2)
	v_fmac_f32_e32 v109, 0x3e38aa3b, v93
	v_cndmask_b32_e64 v109, v2, v109, s[62:63]
	s_waitcnt lgkmcnt(1)
	v_fmac_f32_e32 v110, 0x3e38aa3b, v94
	v_cndmask_b32_e64 v110, v2, v110, s[64:65]
	s_waitcnt lgkmcnt(0)
	v_fmac_f32_e32 v111, 0x3e38aa3b, v95
	v_cndmask_b32_e64 v111, v2, v111, s[66:67]
	s_mov_b64 s[16:17], exec
	v_max_f32_e32 v2, v97, v97
	v_max_f32_e32 v3, v96, v96
	v_max_f32_e32 v2, v3, v2
	v_max_f32_e32 v3, v99, v99
	v_max_f32_e32 v4, v98, v98
	v_max_f32_e32 v3, v4, v3
	v_max_f32_e32 v4, v103, v103
	v_max_f32_e32 v5, v102, v102
	v_max_f32_e32 v4, v5, v4
	v_max3_f32 v4, v100, v101, v4
	v_max3_f32 v2, v2, v3, v4
	v_max_f32_e32 v3, v107, v107
	v_max_f32_e32 v4, v106, v106
	v_max_f32_e32 v3, v4, v3
	v_max_f32_e32 v4, v111, v111
	v_max_f32_e32 v5, v110, v110
	v_max_f32_e32 v4, v5, v4
	v_max3_f32 v3, v104, v105, v3
	v_max3_f32 v4, v108, v109, v4
	v_max3_f32 v2, v2, v3, v4

; DI float shx(float v, int mask, int lane) { return __int_as_float(__builtin_amdgcn_ds_bpermute((lane ^ mask) << 2, __float_as_int(v))); }
; template <int I0, int I1>
; DI void na_softmax(f32x16& sc, f32x16& o0, f32x16& o1, float& mrun, float& lsum, const float* __restrict__ brow_, const int kcb,
;                    const int w0, const int qcol, const float cs, const int lane) {
; #pragma unroll
;   for (int i = I0; i < I1; ++i) {
;     const int kc = kcb + 8 * (i >> 2) + (i & 3);
;     const bool valid = (kc >= w0) && (kc < w0 + 16);
;     const int dx = min(max(kc - qcol, -15), 15) + 15;
;     const float bv = brow_[dx];
;     sc[i] = valid ? sc[i] * cs + bv : -1e30f;
;   }
;   float tmax = sc[I0];
; #pragma unroll
;   for (int i = I0 + 1; i < I1; ++i) tmax = fmaxf(tmax, sc[i]);
;   tmax = fmaxf(tmax, shx(tmax, 32, lane));
;   if (__builtin_amdgcn_ballot_w64(tmax > mrun + 4.f) != 0ull) {
;     const float mnew = fmaxf(mrun, tmax);
;     const float alpha = __builtin_amdgcn_exp2f(mrun - mnew);
;     mrun = mnew;
;     lsum *= alpha;
; #pragma unroll
;     for (int i = 0; i < 16; ++i) { o0[i] *= alpha; o1[i] *= alpha; }
;   }
.LBB0_442:
	s_and_b64 vcc, exec, s[16:17]
	s_cbranch_vccz .LBB0_333
	v_lshl_add_u32 v3, v153, 2, s46
	v_lshl_add_u32 v2, v154, 2, s46
	v_lshl_add_u32 v5, v155, 2, s46
	v_lshl_add_u32 v4, v156, 2, s46
	ds_read_b32 v3, v3 offset:928
	ds_read_b32 v2, v2 offset:928
	ds_read_b32 v5, v5 offset:928
	ds_read_b32 v4, v4 offset:928
	v_mov_b32_e32 v6, 0xf149f2ca
	s_nop 1
	s_waitcnt lgkmcnt(3)
	v_fmac_f32_e32 v3, 0x3e38aa3b, v80
	v_cndmask_b32_e64 v3, v6, v3, s[18:19]
	s_waitcnt lgkmcnt(2)
	v_fmac_f32_e32 v2, 0x3e38aa3b, v81
	v_cndmask_b32_e64 v2, v6, v2, s[68:69]
	s_waitcnt lgkmcnt(1)
	v_fmac_f32_e32 v5, 0x3e38aa3b, v82
	v_cndmask_b32_e64 v5, v6, v5, s[70:71]
	s_waitcnt lgkmcnt(0)
	v_fmac_f32_e32 v4, 0x3e38aa3b, v83
	v_cndmask_b32_e64 v4, v6, v4, s[22:23]
	s_mov_b64 s[16:17], exec
	v_max_f32_e32 v6, v2, v2
	v_max_f32_e32 v7, v3, v3
	v_max_f32_e32 v6, v7, v6
	v_max3_f32 v6, v6, v5, v4
	ds_bpermute_b32 v7, v136, v6
	s_waitcnt lgkmcnt(0)
	v_max_f32_e32 v7, v7, v7
	v_max_f32_e32 v6, v6, v7
	v_add_f32_e32 v7, 4.0, v0
	v_cmp_gt_f32_e32 vcc, v6, v7
	s_cbranch_vccz .LBB0_332
	v_max_f32_e32 v6, v6, v6
	v_max_f32_e32 v7, v0, v0
	v_max_f32_e32 v6, v7, v6
	v_sub_f32_e32 v0, v0, v6
	v_exp_f32_e32 v0, v0
	s_nop 0
	v_mul_f32_e32 v197, v197, v0
	v_pk_mul_f32 v[62:63], v[62:63], v[0:1] op_sel_hi:[1,0]
	v_pk_mul_f32 v[60:61], v[60:61], v[0:1] op_sel_hi:[1,0]
	v_pk_mul_f32 v[58:59], v[58:59], v[0:1] op_sel_hi:[1,0]
	v_pk_mul_f32 v[56:57], v[56:57], v[0:1] op_sel_hi:[1,0]
	v_pk_mul_f32 v[54:55], v[54:55], v[0:1] op_sel_hi:[1,0]
	v_pk_mul_f32 v[52:53], v[52:53], v[0:1] op_sel_hi:[1,0]
	v_pk_mul_f32 v[50:51], v[50:51], v[0:1] op_sel_hi:[1,0]
	v_pk_mul_f32 v[48:49], v[48:49], v[0:1] op_sel_hi:[1,0]
	v_pk_mul_f32 v[78:79], v[78:79], v[0:1] op_sel_hi:[1,0]
	v_pk_mul_f32 v[76:77], v[76:77], v[0:1] op_sel_hi:[1,0]
	v_pk_mul_f32 v[74:75], v[74:75], v[0:1] op_sel_hi:[1,0]
	v_pk_mul_f32 v[72:73], v[72:73], v[0:1] op_sel_hi:[1,0]
	v_pk_mul_f32 v[70:71], v[70:71], v[0:1] op_sel_hi:[1,0]
	v_pk_mul_f32 v[68:69], v[68:69], v[0:1] op_sel_hi:[1,0]
	v_pk_mul_f32 v[66:67], v[66:67], v[0:1] op_sel_hi:[1,0]
	v_pk_mul_f32 v[64:65], v[64:65], v[0:1] op_sel_hi:[1,0]
	v_mov_b32_e32 v0, v6
	s_branch .LBB0_332
